# v36 stack without the branch-free scan select (the scans keep the compiler's exec-mask diamonds)
# baseline (speedup 1.0000x reference)
; __device__ __forceinline__ unsigned pk2(float lo, float hi) { f32x2_pk v = {lo, hi}; bf16x2_pk b = __builtin_convertvector(v, bf16x2_pk); return __builtin_bit_cast(unsigned, b); }
; __device__ __forceinline__ float sigmoidf_(float x) { return __builtin_amdgcn_rcpf(1.0f + __expf(-x)); }
; __device__ __forceinline__ void rg_unpack8(const u32x4 w, float* v) { v[0] = bflo(w.x); v[1] = bfhi(w.x); v[2] = bflo(w.y); v[3] = bfhi(w.y); v[4] = bflo(w.z); v[5] = bfhi(w.z); v[6] = bflo(w.w); v[7] = bfhi(w.w); }
; __device__ __forceinline__ void rg_ab(float ra, float ri, float x, float ba, float bx, float sp, float& a, float& b) {
;     const float r = sigmoidf_(ra + ba), ig = sigmoidf_(ri + bx); const float l2 = r * sp; a = exp2f(l2);
;     const float x2 = 1.3862943611198906f * l2;
;     const float om = x2 > -0.125f ? -x2 * (1.0f + x2 * (0.5f + x2 * (0.16666667f + x2 * (0.041666668f + x2 * 0.0083333338f)))) : 1.0f - __expf(x2);
;     b = __builtin_amdgcn_sqrtf(om) * (ig * x);
; }
; __device__ __forceinline__ void rg_scan2_phase(const bf16_t* RA0, bf16_t* RI0, const bf16_t* RA1, const bf16_t* RI1, const bf16_t* XCV, const float* bap, const float* bxp, const float* lamp, const float* CAR, bf16_t* Gb, int gtid, int ngt) {
;     ...
; #pragma unroll 4
;         for (int i = 0; i < 64; ++i) { const size_t off = (size_t)(row0 + i) * DRNN + 8 * cg;
;             float ra[8], ri[8], xv[8]; rg_unpack8(*(const u32x4*)(RA0 + off), ra); rg_unpack8(*(const u32x4*)(RI0 + off), ri); rg_unpack8(*(const u32x4*)(XCV + off), xv);
; #pragma unroll
;             for (int e = 0; e < 8; ++e) { float a, bb; rg_ab(ra[e], ri[e], xv[e], ba[e], bx[e], sp[e], a, bb); h[e] = a * h[e] + bb; }
;             u32x4 o; o.x = pk2(h[0], h[1]); o.y = pk2(h[2], h[3]); o.z = pk2(h[4], h[5]); o.w = pk2(h[6], h[7]); *(u32x4*)(RI0 + off) = o; }
.LBB0_1251:
	v_lshl_add_u64 v[38:39], v[34:35], 0, s[6:7]
	v_add_co_u32_e32 v16, vcc, 0xe400000, v38
	s_nop 1
	v_addc_co_u32_e32 v17, vcc, 0, v39, vcc
	s_nop 1
	v_mov_b32_e32 v24, v162
	v_mov_b32_e32 v25, v163
	v_mov_b32_e32 v26, v164
	v_mov_b32_e32 v27, v165
	global_load_dwordx4 v[162:165], v[16:17], off offset:2560
	v_add_co_u32_e32 v16, vcc, 0x13e00000, v38
	s_nop 0
	v_lshlrev_b32_e32 v31, 16, v24
	v_addc_co_u32_e32 v17, vcc, 0, v39, vcc
	v_add_co_u32_e32 v20, vcc, 0x8a00000, v38
	global_load_dwordx4 v[16:19], v[16:17], off
	s_nop 0
	v_addc_co_u32_e32 v21, vcc, 0, v39, vcc
	global_load_dwordx4 v[20:23], v[20:21], off
	v_add_f32_e32 v31, v0, v31
	v_mul_f32_e32 v31, 0xbfb8aa3b, v31
	v_exp_f32_e32 v31, v31
	s_nop 0
	v_add_f32_e32 v31, 1.0, v31
	v_rcp_f32_e32 v31, v31
	s_nop 0
	v_mul_f32_e32 v31, v74, v31
	v_mul_f32_e32 v43, 0x3fb17218, v31
	v_cmp_nlt_f32_e32 vcc, s5, v43
	s_and_saveexec_b64 s[2:3], vcc
	s_xor_b64 s[24:25], exec, s[2:3]
	v_mul_f32_e32 v41, 0x3fb8aa3b, v43
	v_exp_f32_e32 v41, v41
	s_nop 0
	v_sub_f32_e32 v41, 1.0, v41
	s_andn2_saveexec_b64 s[24:25], s[24:25]
	v_fmamk_f32 v41, v43, 0x3c088889, v202
	v_fmaak_f32 v41, v43, v41, 0x3e2aaaab
	v_fma_f32 v41, v43, v41, 0.5
	v_fma_f32 v41, v43, v41, 1.0
	v_mul_f32_e64 v41, v41, -v43
	s_or_b64 exec, exec, s[24:25]
	v_and_b32_e32 v24, 0xffff0000, v24
	v_add_f32_e32 v24, v1, v24
	v_mul_f32_e32 v24, 0xbfb8aa3b, v24
	v_exp_f32_e32 v24, v24
	s_nop 0
	v_add_f32_e32 v24, 1.0, v24
	v_rcp_f32_e32 v24, v24
	s_nop 0
	v_mul_f32_e32 v43, v73, v24
	v_mul_f32_e32 v24, 0x3fb17218, v43
	v_cmp_nlt_f32_e32 vcc, s5, v24
	s_and_saveexec_b64 s[2:3], vcc
	s_xor_b64 s[24:25], exec, s[2:3]
	v_mul_f32_e32 v24, 0x3fb8aa3b, v24
	v_exp_f32_e32 v24, v24
	s_nop 0
	v_sub_f32_e32 v59, 1.0, v24
	s_andn2_saveexec_b64 s[24:25], s[24:25]
	v_fmamk_f32 v45, v24, 0x3c088889, v202
	v_fmaak_f32 v45, v24, v45, 0x3e2aaaab
	v_fma_f32 v45, v24, v45, 0.5
	v_fma_f32 v45, v24, v45, 1.0
	v_mul_f32_e64 v59, v45, -v24
	s_or_b64 exec, exec, s[24:25]
	v_lshlrev_b32_e32 v24, 16, v25
	v_add_f32_e32 v24, v2, v24
	v_mul_f32_e32 v24, 0xbfb8aa3b, v24
	v_exp_f32_e32 v24, v24
	s_nop 0
	v_add_f32_e32 v24, 1.0, v24
	v_rcp_f32_e32 v24, v24
	s_nop 0
	v_mul_f32_e32 v45, v71, v24
	v_mul_f32_e32 v24, 0x3fb17218, v45
	v_cmp_nlt_f32_e32 vcc, s5, v24
	s_and_saveexec_b64 s[2:3], vcc
	s_xor_b64 s[24:25], exec, s[2:3]
	v_mul_f32_e32 v24, 0x3fb8aa3b, v24
	v_exp_f32_e32 v24, v24
	s_nop 0
	v_sub_f32_e32 v60, 1.0, v24
	s_andn2_saveexec_b64 s[24:25], s[24:25]
	v_fmamk_f32 v47, v24, 0x3c088889, v202
	v_fmaak_f32 v47, v24, v47, 0x3e2aaaab
	v_fma_f32 v47, v24, v47, 0.5
	v_fma_f32 v47, v24, v47, 1.0
	v_mul_f32_e64 v60, v47, -v24
	s_or_b64 exec, exec, s[24:25]
	v_and_b32_e32 v24, 0xffff0000, v25
	v_add_f32_e32 v24, v3, v24
	v_mul_f32_e32 v24, 0xbfb8aa3b, v24
	v_exp_f32_e32 v24, v24
	s_nop 0
	v_add_f32_e32 v24, 1.0, v24
	v_rcp_f32_e32 v24, v24
	s_nop 0
	v_mul_f32_e32 v61, v70, v24
	v_mul_f32_e32 v24, 0x3fb17218, v61
	v_cmp_nlt_f32_e32 vcc, s5, v24
	s_and_saveexec_b64 s[2:3], vcc
	s_xor_b64 s[24:25], exec, s[2:3]
	v_mul_f32_e32 v24, 0x3fb8aa3b, v24
	v_exp_f32_e32 v24, v24
	s_nop 0
	v_sub_f32_e32 v51, 1.0, v24
	s_andn2_saveexec_b64 s[24:25], s[24:25]
	v_fmamk_f32 v25, v24, 0x3c088889, v202
	v_fmaak_f32 v25, v24, v25, 0x3e2aaaab
	v_fma_f32 v25, v24, v25, 0.5
	v_fma_f32 v25, v24, v25, 1.0
	v_mul_f32_e64 v51, v25, -v24
	s_or_b64 exec, exec, s[24:25]
	v_lshlrev_b32_e32 v24, 16, v26
	v_add_f32_e32 v24, v8, v24
	v_mul_f32_e32 v24, 0xbfb8aa3b, v24
	v_exp_f32_e32 v24, v24
	s_nop 0
	v_add_f32_e32 v24, 1.0, v24
	v_rcp_f32_e32 v24, v24
	s_nop 0
	v_mul_f32_e32 v56, v69, v24
	v_mul_f32_e32 v24, 0x3fb17218, v56
	v_cmp_nlt_f32_e32 vcc, s5, v24
	s_and_saveexec_b64 s[2:3], vcc
	s_xor_b64 s[24:25], exec, s[2:3]
	v_mul_f32_e32 v24, 0x3fb8aa3b, v24
	v_exp_f32_e32 v24, v24
	s_nop 0
	v_sub_f32_e32 v49, 1.0, v24
	s_andn2_saveexec_b64 s[24:25], s[24:25]
	v_fmamk_f32 v25, v24, 0x3c088889, v202
	v_fmaak_f32 v25, v24, v25, 0x3e2aaaab
	v_fma_f32 v25, v24, v25, 0.5
	v_fma_f32 v25, v24, v25, 1.0
	v_mul_f32_e64 v49, v25, -v24
	s_or_b64 exec, exec, s[24:25]
	v_and_b32_e32 v24, 0xffff0000, v26
	v_add_f32_e32 v24, v9, v24
	v_mul_f32_e32 v24, 0xbfb8aa3b, v24
	v_exp_f32_e32 v24, v24
	s_nop 0
	v_add_f32_e32 v24, 1.0, v24
	v_rcp_f32_e32 v24, v24
	s_nop 0
	v_mul_f32_e32 v57, v68, v24
	v_mul_f32_e32 v24, 0x3fb17218, v57
	v_cmp_nlt_f32_e32 vcc, s5, v24
	s_and_saveexec_b64 s[2:3], vcc
	s_xor_b64 s[24:25], exec, s[2:3]
	v_mul_f32_e32 v24, 0x3fb8aa3b, v24
	v_exp_f32_e32 v24, v24
	s_nop 0
	v_sub_f32_e32 v47, 1.0, v24
	s_andn2_saveexec_b64 s[24:25], s[24:25]
	v_fmamk_f32 v25, v24, 0x3c088889, v202
	v_fmaak_f32 v25, v24, v25, 0x3e2aaaab
	v_fma_f32 v25, v24, v25, 0.5
	v_fma_f32 v25, v24, v25, 1.0
	v_mul_f32_e64 v47, v25, -v24
	s_or_b64 exec, exec, s[24:25]
	v_lshlrev_b32_e32 v24, 16, v27
	v_add_f32_e32 v24, v10, v24
	v_mul_f32_e32 v24, 0xbfb8aa3b, v24
	v_exp_f32_e32 v24, v24
	s_nop 0
	v_add_f32_e32 v24, 1.0, v24
	v_rcp_f32_e32 v24, v24
	s_nop 0
	v_mul_f32_e32 v54, v67, v24
	v_mul_f32_e32 v24, 0x3fb17218, v54
	v_cmp_nlt_f32_e32 vcc, s5, v24
	s_and_saveexec_b64 s[2:3], vcc
	s_xor_b64 s[24:25], exec, s[2:3]
	v_mul_f32_e32 v24, 0x3fb8aa3b, v24
	v_exp_f32_e32 v24, v24
	s_nop 0
	v_sub_f32_e32 v53, 1.0, v24
	s_andn2_saveexec_b64 s[24:25], s[24:25]
	v_fmamk_f32 v25, v24, 0x3c088889, v202
	v_fmaak_f32 v25, v24, v25, 0x3e2aaaab
	v_fma_f32 v25, v24, v25, 0.5
	v_fma_f32 v25, v24, v25, 1.0
	v_mul_f32_e64 v53, v25, -v24
	s_or_b64 exec, exec, s[24:25]
	v_and_b32_e32 v24, 0xffff0000, v27
	v_add_f32_e32 v24, v11, v24
	v_mul_f32_e32 v24, 0xbfb8aa3b, v24
	v_exp_f32_e32 v24, v24
	s_nop 0
	v_add_f32_e32 v24, 1.0, v24
	v_rcp_f32_e32 v24, v24
	s_nop 0
	v_mul_f32_e32 v27, v75, v24
	v_mul_f32_e32 v24, 0x3fb17218, v27
	v_cmp_nlt_f32_e32 vcc, s5, v24
	s_and_saveexec_b64 s[2:3], vcc
	s_xor_b64 s[24:25], exec, s[2:3]
	v_mul_f32_e32 v24, 0x3fb8aa3b, v24
	v_exp_f32_e32 v24, v24
	s_nop 0
	v_sub_f32_e32 v26, 1.0, v24
	s_andn2_saveexec_b64 s[24:25], s[24:25]
	v_fmamk_f32 v25, v24, 0x3c088889, v202
	v_fmaak_f32 v25, v24, v25, 0x3e2aaaab
	v_fma_f32 v25, v24, v25, 0.5
	v_fma_f32 v25, v24, v25, 1.0
	v_mul_f32_e64 v26, v25, -v24
	s_or_b64 exec, exec, s[24:25]
	v_cmp_gt_f32_e32 vcc, s82, v54
	s_mov_b64 s[2:3], 0x13e00000
	v_lshl_add_u64 v[24:25], v[38:39], 0, s[2:3]
	v_cndmask_b32_e32 v62, 0, v221, vcc
	v_add_f32_e32 v54, v54, v62
	v_exp_f32_e32 v54, v54
	v_cndmask_b32_e32 v55, 0, v220, vcc
	s_waitcnt vmcnt(0)
; __device__ __forceinline__ unsigned pk2(float lo, float hi) { f32x2_pk v = {lo, hi}; bf16x2_pk b = __builtin_convertvector(v, bf16x2_pk); return __builtin_bit_cast(unsigned, b); }
; __device__ __forceinline__ float sigmoidf_(float x) { return __builtin_amdgcn_rcpf(1.0f + __expf(-x)); }
; __device__ __forceinline__ void rg_unpack8(const u32x4 w, float* v) { v[0] = bflo(w.x); v[1] = bfhi(w.x); v[2] = bflo(w.y); v[3] = bfhi(w.y); v[4] = bflo(w.z); v[5] = bfhi(w.z); v[6] = bflo(w.w); v[7] = bfhi(w.w); }
; __device__ __forceinline__ void rg_ab(float ra, float ri, float x, float ba, float bx, float sp, float& a, float& b) {
;     const float r = sigmoidf_(ra + ba), ig = sigmoidf_(ri + bx); const float l2 = r * sp; a = exp2f(l2);
;     const float x2 = 1.3862943611198906f * l2;
;     const float om = x2 > -0.125f ? -x2 * (1.0f + x2 * (0.5f + x2 * (0.16666667f + x2 * (0.041666668f + x2 * 0.0083333338f)))) : 1.0f - __expf(x2);
;     b = __builtin_amdgcn_sqrtf(om) * (ig * x);
; }
; __device__ __forceinline__ void rg_scan2_phase(const bf16_t* RA0, bf16_t* RI0, const bf16_t* RA1, const bf16_t* RI1, const bf16_t* XCV, const float* bap, const float* bxp, const float* lamp, const float* CAR, bf16_t* Gb, int gtid, int ngt) {
;     ...
; #pragma unroll 4
;         for (int i = 0; i < 64; ++i) { const size_t off = (size_t)(row0 + i) * DRNN + 8 * cg;
;             float ra[8], ri[8], xv[8]; rg_unpack8(*(const u32x4*)(RA0 + off), ra); rg_unpack8(*(const u32x4*)(RI0 + off), ri); rg_unpack8(*(const u32x4*)(XCV + off), xv);
; #pragma unroll
;             for (int e = 0; e < 8; ++e) { float a, bb; rg_ab(ra[e], ri[e], xv[e], ba[e], bx[e], sp[e], a, bb); h[e] = a * h[e] + bb; }
;             u32x4 o; o.x = pk2(h[0], h[1]); o.y = pk2(h[2], h[3]); o.z = pk2(h[4], h[5]); o.w = pk2(h[6], h[7]); *(u32x4*)(RI0 + off) = o; }
	v_lshlrev_b32_e32 v62, 16, v23
	v_cmp_gt_f32_e32 vcc, s82, v27
	v_ldexp_f32 v54, v54, v55
	v_lshlrev_b32_e32 v55, 16, v19
	v_add_f32_e32 v55, v14, v55
	v_mul_f32_e32 v55, 0xbfb8aa3b, v55
	v_exp_f32_e32 v55, v55
	s_mov_b32 s1, 0xe400000
	v_add_f32_e32 v55, 1.0, v55
	v_rcp_f32_e32 v63, v55
	v_sqrt_f32_e32 v55, v53
	v_mul_f32_e32 v53, v63, v62
	v_mul_f32_e32 v62, v53, v55
	v_pk_fma_f32 v[54:55], v[52:53], v[54:55], v[62:63] op_sel_hi:[1,1,0]
	v_cndmask_b32_e32 v53, 0, v221, vcc
	v_add_f32_e32 v27, v27, v53
	v_exp_f32_e32 v27, v27
	v_cndmask_b32_e32 v52, 0, v220, vcc
	v_cmp_gt_f32_e32 vcc, s82, v57
	v_sqrt_f32_e32 v53, v47
	v_ldexp_f32 v62, v27, v52
	v_cndmask_b32_e32 v52, 0, v221, vcc
	v_add_f32_e32 v52, v57, v52
	v_exp_f32_e32 v52, v52
	v_cndmask_b32_e32 v27, 0, v220, vcc
	v_and_b32_e32 v55, 0xffff0000, v22
	v_cmp_gt_f32_e32 vcc, s82, v56
	v_ldexp_f32 v52, v52, v27
	v_and_b32_e32 v27, 0xffff0000, v18
	v_add_f32_e32 v27, v13, v27
	v_mul_f32_e32 v27, 0xbfb8aa3b, v27
	v_exp_f32_e32 v27, v27
	v_lshlrev_b32_e32 v18, 16, v18
	v_add_f32_e32 v18, v12, v18
	v_mul_f32_e32 v18, 0xbfb8aa3b, v18
	v_add_f32_e32 v27, 1.0, v27
	v_exp_f32_e32 v18, v18
	v_rcp_f32_e32 v27, v27
	v_lshlrev_b32_e32 v22, 16, v22
	v_sqrt_f32_e32 v63, v26
	v_add_f32_e32 v18, 1.0, v18
	v_mul_f32_e32 v47, v27, v55
	v_rcp_f32_e32 v18, v18
	v_mul_f32_e32 v76, v47, v53
	v_pk_fma_f32 v[52:53], v[46:47], v[52:53], v[76:77] op_sel_hi:[1,1,0]
	v_cndmask_b32_e32 v46, 0, v221, vcc
	v_cndmask_b32_e32 v27, 0, v220, vcc
	v_add_f32_e32 v46, v56, v46
	v_cmp_gt_f32_e32 vcc, s82, v61
	v_exp_f32_e32 v46, v46
	v_sqrt_f32_e32 v47, v49
	v_mul_f32_e32 v49, v18, v22
	v_cndmask_b32_e32 v22, 0, v221, vcc
	v_add_f32_e32 v22, v61, v22
	v_exp_f32_e32 v22, v22
	v_ldexp_f32 v46, v46, v27
	v_mul_f32_e32 v18, v49, v47
	v_pk_fma_f32 v[56:57], v[48:49], v[46:47], v[18:19] op_sel_hi:[1,1,0]
	v_cndmask_b32_e32 v18, 0, v220, vcc
	v_ldexp_f32 v46, v22, v18
	v_and_b32_e32 v18, 0xffff0000, v17
	v_add_f32_e32 v18, v7, v18
	v_mul_f32_e32 v18, 0xbfb8aa3b, v18
	v_exp_f32_e32 v18, v18
	v_lshlrev_b32_e32 v17, 16, v17
	v_add_f32_e32 v17, v6, v17
	v_mul_f32_e32 v17, 0xbfb8aa3b, v17
	v_add_f32_e32 v18, 1.0, v18
	v_rcp_f32_e32 v18, v18
	v_exp_f32_e32 v17, v17
	v_and_b32_e32 v22, 0xffff0000, v21
	v_sqrt_f32_e32 v47, v51
	v_cmp_gt_f32_e32 vcc, s82, v45
	v_mul_f32_e32 v51, v18, v22
	v_add_f32_e32 v17, 1.0, v17
	v_cndmask_b32_e32 v22, 0, v221, vcc
	v_add_f32_e32 v22, v45, v22
	v_exp_f32_e32 v22, v22
	v_mul_f32_e32 v18, v51, v47
	v_rcp_f32_e32 v17, v17
	v_pk_fma_f32 v[50:51], v[50:51], v[46:47], v[18:19] op_sel_hi:[1,1,0]
	v_sqrt_f32_e32 v47, v60
	v_cndmask_b32_e32 v18, 0, v220, vcc
	v_ldexp_f32 v46, v22, v18
	v_lshlrev_b32_e32 v18, 16, v21
	v_mul_f32_e32 v45, v17, v18
	v_mul_f32_e32 v18, v45, v47
	v_cmp_gt_f32_e32 vcc, s82, v43
	v_pk_fma_f32 v[48:49], v[44:45], v[46:47], v[18:19] op_sel_hi:[1,1,0]
	v_sqrt_f32_e32 v45, v59
	v_cndmask_b32_e32 v18, 0, v221, vcc
	v_add_f32_e32 v18, v43, v18
	v_exp_f32_e32 v18, v18
	v_cndmask_b32_e32 v17, 0, v220, vcc
	v_cmp_gt_f32_e32 vcc, s82, v31
	v_ldexp_f32 v44, v18, v17
	v_and_b32_e32 v17, 0xffff0000, v16
	v_add_f32_e32 v17, v5, v17
	v_mul_f32_e32 v17, 0xbfb8aa3b, v17
	v_exp_f32_e32 v17, v17
	v_and_b32_e32 v18, 0xffff0000, v20
	v_add_f32_e32 v17, 1.0, v17
	v_rcp_f32_e32 v17, v17
	s_nop 0
	v_mul_f32_e32 v43, v17, v18
	v_lshlrev_b32_e32 v17, 16, v16
	v_mul_f32_e32 v18, v42, v44
	v_add_f32_e32 v17, v4, v17
	v_pk_fma_f32 v[46:47], v[42:43], v[44:45], v[18:19] op_sel_hi:[1,1,0]
	v_lshlrev_b32_e32 v18, 16, v20
	v_cndmask_b32_e32 v20, 0, v221, vcc
	v_mul_f32_e32 v17, 0xbfb8aa3b, v17
	v_add_f32_e32 v20, v31, v20
	v_exp_f32_e32 v17, v17
	v_exp_f32_e32 v20, v20
	v_cndmask_b32_e32 v16, 0, v220, vcc
	v_add_f32_e32 v17, 1.0, v17
	v_ldexp_f32 v16, v20, v16
	v_rcp_f32_e32 v20, v17
	v_sqrt_f32_e32 v17, v41
	v_mul_f32_e32 v41, v20, v18
	v_mul_f32_e32 v18, v41, v17
	v_pk_fma_f32 v[42:43], v[40:41], v[16:17], v[18:19] op_sel_hi:[1,1,0]
	v_and_b32_e32 v16, 0xffff0000, v19
	v_add_f32_e32 v16, v15, v16
	v_mul_f32_e32 v16, 0xbfb8aa3b, v16
	v_exp_f32_e32 v16, v16
	v_and_b32_e32 v17, 0xffff0000, v23
	v_cvt_pk_bf16_f32 v18, v56, v52
	v_add_f32_e32 v16, 1.0, v16
	v_rcp_f32_e32 v16, v16
	s_nop 0
	v_mul_f32_e32 v59, v16, v17
	v_mul_f32_e32 v16, v59, v63
	v_pk_fma_f32 v[40:41], v[58:59], v[62:63], v[16:17] op_sel_hi:[1,1,0]
	v_cvt_pk_bf16_f32 v16, v42, v47
	v_cvt_pk_bf16_f32 v17, v48, v50
	v_cvt_pk_bf16_f32 v19, v54, v40
	global_store_dwordx4 v[24:25], v[16:19], off
	s_nop 1
	v_add_co_u32_e32 v16, vcc, s1, v38
	s_mov_b32 s1, 0x13e00000
	s_nop 0
	v_addc_co_u32_e32 v17, vcc, 0, v39, vcc
	s_nop 1
	v_mov_b32_e32 v24, v162
	v_mov_b32_e32 v25, v163
	v_mov_b32_e32 v26, v164
	v_mov_b32_e32 v27, v165
	v_lshl_add_u64 v[166:167], v[16:17], 0, s[100:101]
	global_load_dwordx4 v[162:165], v[166:167], off offset:1024
	v_add_co_u32_e32 v16, vcc, s1, v38
	s_nop 0
	v_lshlrev_b32_e32 v31, 16, v24
	v_addc_co_u32_e32 v17, vcc, 0, v39, vcc
	v_add_co_u32_e32 v20, vcc, 0x8a00000, v38
	global_load_dwordx4 v[16:19], v[16:17], off offset:2560
	s_nop 0
	v_addc_co_u32_e32 v21, vcc, 0, v39, vcc
	global_load_dwordx4 v[20:23], v[20:21], off offset:2560
	v_add_f32_e32 v31, v0, v31
	v_mul_f32_e32 v31, 0xbfb8aa3b, v31
	v_exp_f32_e32 v31, v31
	s_nop 0
	v_add_f32_e32 v31, 1.0, v31
	v_rcp_f32_e32 v31, v31
	s_nop 0
	v_mul_f32_e32 v31, v74, v31
	v_mul_f32_e32 v43, 0x3fb17218, v31
	v_cmp_nlt_f32_e32 vcc, s5, v43
	s_and_saveexec_b64 s[2:3], vcc
	s_xor_b64 s[24:25], exec, s[2:3]
	v_mul_f32_e32 v41, 0x3fb8aa3b, v43
	v_exp_f32_e32 v41, v41
	s_nop 0
	v_sub_f32_e32 v41, 1.0, v41
	s_andn2_saveexec_b64 s[24:25], s[24:25]
	v_fmamk_f32 v41, v43, 0x3c088889, v202
; __device__ __forceinline__ unsigned pk2(float lo, float hi) { f32x2_pk v = {lo, hi}; bf16x2_pk b = __builtin_convertvector(v, bf16x2_pk); return __builtin_bit_cast(unsigned, b); }
; __device__ __forceinline__ float sigmoidf_(float x) { return __builtin_amdgcn_rcpf(1.0f + __expf(-x)); }
; __device__ __forceinline__ void rg_unpack8(const u32x4 w, float* v) { v[0] = bflo(w.x); v[1] = bfhi(w.x); v[2] = bflo(w.y); v[3] = bfhi(w.y); v[4] = bflo(w.z); v[5] = bfhi(w.z); v[6] = bflo(w.w); v[7] = bfhi(w.w); }
; __device__ __forceinline__ void rg_ab(float ra, float ri, float x, float ba, float bx, float sp, float& a, float& b) {
;     const float r = sigmoidf_(ra + ba), ig = sigmoidf_(ri + bx); const float l2 = r * sp; a = exp2f(l2);
;     const float x2 = 1.3862943611198906f * l2;
;     const float om = x2 > -0.125f ? -x2 * (1.0f + x2 * (0.5f + x2 * (0.16666667f + x2 * (0.041666668f + x2 * 0.0083333338f)))) : 1.0f - __expf(x2);
;     b = __builtin_amdgcn_sqrtf(om) * (ig * x);
; }
; __device__ __forceinline__ void rg_scan2_phase(const bf16_t* RA0, bf16_t* RI0, const bf16_t* RA1, const bf16_t* RI1, const bf16_t* XCV, const float* bap, const float* bxp, const float* lamp, const float* CAR, bf16_t* Gb, int gtid, int ngt) {
;     ...
; #pragma unroll 4
;         for (int i = 0; i < 64; ++i) { const size_t off = (size_t)(row0 + i) * DRNN + 8 * cg;
;             float ra[8], ri[8], xv[8]; rg_unpack8(*(const u32x4*)(RA0 + off), ra); rg_unpack8(*(const u32x4*)(RI0 + off), ri); rg_unpack8(*(const u32x4*)(XCV + off), xv);
; #pragma unroll
;             for (int e = 0; e < 8; ++e) { float a, bb; rg_ab(ra[e], ri[e], xv[e], ba[e], bx[e], sp[e], a, bb); h[e] = a * h[e] + bb; }
;             u32x4 o; o.x = pk2(h[0], h[1]); o.y = pk2(h[2], h[3]); o.z = pk2(h[4], h[5]); o.w = pk2(h[6], h[7]); *(u32x4*)(RI0 + off) = o; }
	v_fmaak_f32 v41, v43, v41, 0x3e2aaaab
	v_fma_f32 v41, v43, v41, 0.5
	v_fma_f32 v41, v43, v41, 1.0
	v_mul_f32_e64 v41, v41, -v43
	s_or_b64 exec, exec, s[24:25]
	v_and_b32_e32 v24, 0xffff0000, v24
	v_add_f32_e32 v24, v1, v24
	v_mul_f32_e32 v24, 0xbfb8aa3b, v24
	v_exp_f32_e32 v24, v24
	s_nop 0
	v_add_f32_e32 v24, 1.0, v24
	v_rcp_f32_e32 v24, v24
	s_nop 0
	v_mul_f32_e32 v43, v73, v24
	v_mul_f32_e32 v24, 0x3fb17218, v43
	v_cmp_nlt_f32_e32 vcc, s5, v24
	s_and_saveexec_b64 s[2:3], vcc
	s_xor_b64 s[24:25], exec, s[2:3]
	v_mul_f32_e32 v24, 0x3fb8aa3b, v24
	v_exp_f32_e32 v24, v24
	s_nop 0
	v_sub_f32_e32 v46, 1.0, v24
	s_andn2_saveexec_b64 s[24:25], s[24:25]
	v_fmamk_f32 v44, v24, 0x3c088889, v202
	v_fmaak_f32 v44, v24, v44, 0x3e2aaaab
	v_fma_f32 v44, v24, v44, 0.5
	v_fma_f32 v44, v24, v44, 1.0
	v_mul_f32_e64 v46, v44, -v24
	s_or_b64 exec, exec, s[24:25]
	v_lshlrev_b32_e32 v24, 16, v25
	v_add_f32_e32 v24, v2, v24
	v_mul_f32_e32 v24, 0xbfb8aa3b, v24
	v_exp_f32_e32 v24, v24
	s_nop 0
	v_add_f32_e32 v24, 1.0, v24
	v_rcp_f32_e32 v24, v24
	s_nop 0
	v_mul_f32_e32 v49, v71, v24
	v_mul_f32_e32 v24, 0x3fb17218, v49
	v_cmp_nlt_f32_e32 vcc, s5, v24
	s_and_saveexec_b64 s[2:3], vcc
	s_xor_b64 s[24:25], exec, s[2:3]
	v_mul_f32_e32 v24, 0x3fb8aa3b, v24
	v_exp_f32_e32 v24, v24
	s_nop 0
	v_sub_f32_e32 v58, 1.0, v24
	s_andn2_saveexec_b64 s[24:25], s[24:25]
	v_fmamk_f32 v44, v24, 0x3c088889, v202
	v_fmaak_f32 v44, v24, v44, 0x3e2aaaab
	v_fma_f32 v44, v24, v44, 0.5
	v_fma_f32 v44, v24, v44, 1.0
	v_mul_f32_e64 v58, v44, -v24
	s_or_b64 exec, exec, s[24:25]
	v_and_b32_e32 v24, 0xffff0000, v25
	v_add_f32_e32 v24, v3, v24
	v_mul_f32_e32 v24, 0xbfb8aa3b, v24
	v_exp_f32_e32 v24, v24
	s_nop 0
	v_add_f32_e32 v24, 1.0, v24
	v_rcp_f32_e32 v24, v24
	s_nop 0
	v_mul_f32_e32 v59, v70, v24
	v_mul_f32_e32 v24, 0x3fb17218, v59
	v_cmp_nlt_f32_e32 vcc, s5, v24
	s_and_saveexec_b64 s[2:3], vcc
	s_xor_b64 s[24:25], exec, s[2:3]
	v_mul_f32_e32 v24, 0x3fb8aa3b, v24
	v_exp_f32_e32 v24, v24
	s_nop 0
	v_sub_f32_e32 v51, 1.0, v24
	s_andn2_saveexec_b64 s[24:25], s[24:25]
	v_fmamk_f32 v25, v24, 0x3c088889, v202
	v_fmaak_f32 v25, v24, v25, 0x3e2aaaab
	v_fma_f32 v25, v24, v25, 0.5
	v_fma_f32 v25, v24, v25, 1.0
	v_mul_f32_e64 v51, v25, -v24
	s_or_b64 exec, exec, s[24:25]
	v_lshlrev_b32_e32 v24, 16, v26
	v_add_f32_e32 v24, v8, v24
	v_mul_f32_e32 v24, 0xbfb8aa3b, v24
	v_exp_f32_e32 v24, v24
	s_nop 0
	v_add_f32_e32 v24, 1.0, v24
	v_rcp_f32_e32 v24, v24
	s_nop 0
	v_mul_f32_e32 v45, v69, v24
	v_mul_f32_e32 v24, 0x3fb17218, v45
	v_cmp_nlt_f32_e32 vcc, s5, v24
	s_and_saveexec_b64 s[2:3], vcc
	s_xor_b64 s[24:25], exec, s[2:3]
	v_mul_f32_e32 v24, 0x3fb8aa3b, v24
	v_exp_f32_e32 v24, v24
	s_nop 0
	v_sub_f32_e32 v44, 1.0, v24
	s_andn2_saveexec_b64 s[24:25], s[24:25]
	v_fmamk_f32 v25, v24, 0x3c088889, v202
	v_fmaak_f32 v25, v24, v25, 0x3e2aaaab
	v_fma_f32 v25, v24, v25, 0.5
	v_fma_f32 v25, v24, v25, 1.0
	v_mul_f32_e64 v44, v25, -v24
	s_or_b64 exec, exec, s[24:25]
	v_and_b32_e32 v24, 0xffff0000, v26
	v_add_f32_e32 v24, v9, v24
	v_mul_f32_e32 v24, 0xbfb8aa3b, v24
	v_exp_f32_e32 v24, v24
	s_nop 0
	v_add_f32_e32 v24, 1.0, v24
	v_rcp_f32_e32 v24, v24
	s_nop 0
	v_mul_f32_e32 v57, v68, v24
	v_mul_f32_e32 v24, 0x3fb17218, v57
	v_cmp_nlt_f32_e32 vcc, s5, v24
	s_and_saveexec_b64 s[2:3], vcc
	s_xor_b64 s[24:25], exec, s[2:3]
	v_mul_f32_e32 v24, 0x3fb8aa3b, v24
	v_exp_f32_e32 v24, v24
	s_nop 0
	v_sub_f32_e32 v53, 1.0, v24
	s_andn2_saveexec_b64 s[24:25], s[24:25]
	v_fmamk_f32 v25, v24, 0x3c088889, v202
	v_fmaak_f32 v25, v24, v25, 0x3e2aaaab
	v_fma_f32 v25, v24, v25, 0.5
	v_fma_f32 v25, v24, v25, 1.0
	v_mul_f32_e64 v53, v25, -v24
	s_or_b64 exec, exec, s[24:25]
	v_lshlrev_b32_e32 v24, 16, v27
	v_add_f32_e32 v24, v10, v24
	v_mul_f32_e32 v24, 0xbfb8aa3b, v24
	v_exp_f32_e32 v24, v24
	s_nop 0
	v_add_f32_e32 v24, 1.0, v24
	v_rcp_f32_e32 v24, v24
	s_nop 0
	v_mul_f32_e32 v60, v67, v24
	v_mul_f32_e32 v24, 0x3fb17218, v60
	v_cmp_nlt_f32_e32 vcc, s5, v24
	s_and_saveexec_b64 s[2:3], vcc
	s_xor_b64 s[24:25], exec, s[2:3]
	v_mul_f32_e32 v24, 0x3fb8aa3b, v24
	v_exp_f32_e32 v24, v24
	s_nop 0
	v_sub_f32_e32 v55, 1.0, v24
	s_andn2_saveexec_b64 s[24:25], s[24:25]
	v_fmamk_f32 v25, v24, 0x3c088889, v202
	v_fmaak_f32 v25, v24, v25, 0x3e2aaaab
	v_fma_f32 v25, v24, v25, 0.5
	v_fma_f32 v25, v24, v25, 1.0
	v_mul_f32_e64 v55, v25, -v24
	s_or_b64 exec, exec, s[24:25]
	v_and_b32_e32 v24, 0xffff0000, v27
	v_add_f32_e32 v24, v11, v24
	v_mul_f32_e32 v24, 0xbfb8aa3b, v24
	v_exp_f32_e32 v24, v24
	s_nop 0
	v_add_f32_e32 v24, 1.0, v24
	v_rcp_f32_e32 v24, v24
	s_nop 0
	v_mul_f32_e32 v27, v75, v24
	v_mul_f32_e32 v24, 0x3fb17218, v27
	v_cmp_nlt_f32_e32 vcc, s5, v24
	s_and_saveexec_b64 s[2:3], vcc
	s_xor_b64 s[24:25], exec, s[2:3]
	v_mul_f32_e32 v24, 0x3fb8aa3b, v24
	v_exp_f32_e32 v24, v24
	s_nop 0
	v_sub_f32_e32 v26, 1.0, v24
	s_andn2_saveexec_b64 s[24:25], s[24:25]
	v_fmamk_f32 v25, v24, 0x3c088889, v202
	v_fmaak_f32 v25, v24, v25, 0x3e2aaaab
	v_fma_f32 v25, v24, v25, 0.5
	v_fma_f32 v25, v24, v25, 1.0
	v_mul_f32_e64 v26, v25, -v24
	s_or_b64 exec, exec, s[24:25]
	v_cmp_gt_f32_e32 vcc, s82, v60
	v_sqrt_f32_e32 v77, v26
	s_mov_b32 s1, 0xe401000
	v_cndmask_b32_e32 v62, 0, v221, vcc
	v_add_f32_e32 v60, v60, v62
	v_exp_f32_e32 v60, v60
	v_cndmask_b32_e32 v61, 0, v220, vcc
	s_waitcnt vmcnt(0)
; __device__ __forceinline__ unsigned pk2(float lo, float hi) { f32x2_pk v = {lo, hi}; bf16x2_pk b = __builtin_convertvector(v, bf16x2_pk); return __builtin_bit_cast(unsigned, b); }
; __device__ __forceinline__ float sigmoidf_(float x) { return __builtin_amdgcn_rcpf(1.0f + __expf(-x)); }
; __device__ __forceinline__ void rg_unpack8(const u32x4 w, float* v) { v[0] = bflo(w.x); v[1] = bfhi(w.x); v[2] = bflo(w.y); v[3] = bfhi(w.y); v[4] = bflo(w.z); v[5] = bfhi(w.z); v[6] = bflo(w.w); v[7] = bfhi(w.w); }
; __device__ __forceinline__ void rg_ab(float ra, float ri, float x, float ba, float bx, float sp, float& a, float& b) {
;     const float r = sigmoidf_(ra + ba), ig = sigmoidf_(ri + bx); const float l2 = r * sp; a = exp2f(l2);
;     const float x2 = 1.3862943611198906f * l2;
;     const float om = x2 > -0.125f ? -x2 * (1.0f + x2 * (0.5f + x2 * (0.16666667f + x2 * (0.041666668f + x2 * 0.0083333338f)))) : 1.0f - __expf(x2);
;     b = __builtin_amdgcn_sqrtf(om) * (ig * x);
; }
; __device__ __forceinline__ void rg_scan2_phase(const bf16_t* RA0, bf16_t* RI0, const bf16_t* RA1, const bf16_t* RI1, const bf16_t* XCV, const float* bap, const float* bxp, const float* lamp, const float* CAR, bf16_t* Gb, int gtid, int ngt) {
;     ...
; #pragma unroll 4
;         for (int i = 0; i < 64; ++i) { const size_t off = (size_t)(row0 + i) * DRNN + 8 * cg;
;             float ra[8], ri[8], xv[8]; rg_unpack8(*(const u32x4*)(RA0 + off), ra); rg_unpack8(*(const u32x4*)(RI0 + off), ri); rg_unpack8(*(const u32x4*)(XCV + off), xv);
; #pragma unroll
;             for (int e = 0; e < 8; ++e) { float a, bb; rg_ab(ra[e], ri[e], xv[e], ba[e], bx[e], sp[e], a, bb); h[e] = a * h[e] + bb; }
;             u32x4 o; o.x = pk2(h[0], h[1]); o.y = pk2(h[2], h[3]); o.z = pk2(h[4], h[5]); o.w = pk2(h[6], h[7]); *(u32x4*)(RI0 + off) = o; }
	v_lshlrev_b32_e32 v62, 16, v23
	v_cmp_gt_f32_e32 vcc, s82, v27
	v_ldexp_f32 v60, v60, v61
	v_lshlrev_b32_e32 v61, 16, v19
	v_add_f32_e32 v61, v14, v61
	v_mul_f32_e32 v61, 0xbfb8aa3b, v61
	v_exp_f32_e32 v61, v61
	s_mov_b64 s[2:3], 0x13e00a00
	v_lshl_add_u64 v[24:25], v[38:39], 0, s[2:3]
	v_add_f32_e32 v61, 1.0, v61
	v_rcp_f32_e32 v63, v61
	v_sqrt_f32_e32 v61, v55
	v_mul_f32_e32 v55, v63, v62
	v_mul_f32_e32 v62, v55, v61
	v_pk_fma_f32 v[54:55], v[54:55], v[60:61], v[62:63] op_sel_hi:[1,1,0]
	v_cndmask_b32_e32 v60, 0, v221, vcc
	v_add_f32_e32 v27, v27, v60
	v_exp_f32_e32 v27, v27
	v_cndmask_b32_e32 v55, 0, v220, vcc
	v_cmp_gt_f32_e32 vcc, s82, v57
	v_sqrt_f32_e32 v61, v53
	v_ldexp_f32 v76, v27, v55
	v_cndmask_b32_e32 v55, 0, v221, vcc
	v_add_f32_e32 v55, v57, v55
	v_exp_f32_e32 v55, v55
	v_cndmask_b32_e32 v27, 0, v220, vcc
	v_cmp_gt_f32_e32 vcc, s82, v45
	v_ldexp_f32 v60, v55, v27
	v_and_b32_e32 v27, 0xffff0000, v18
	v_add_f32_e32 v27, v13, v27
	v_mul_f32_e32 v27, 0xbfb8aa3b, v27
	v_exp_f32_e32 v27, v27
	v_lshlrev_b32_e32 v18, 16, v18
	v_add_f32_e32 v18, v12, v18
	v_mul_f32_e32 v18, 0xbfb8aa3b, v18
	v_add_f32_e32 v27, 1.0, v27
	v_rcp_f32_e32 v27, v27
	v_exp_f32_e32 v18, v18
	v_and_b32_e32 v55, 0xffff0000, v22
	v_lshlrev_b32_e32 v22, 16, v22
	v_mul_f32_e32 v53, v27, v55
	v_add_f32_e32 v18, 1.0, v18
	v_mul_f32_e32 v62, v53, v61
	v_rcp_f32_e32 v18, v18
	v_pk_fma_f32 v[52:53], v[52:53], v[60:61], v[62:63] op_sel_hi:[1,1,0]
	v_cndmask_b32_e32 v27, 0, v220, vcc
	v_cndmask_b32_e32 v53, 0, v221, vcc
	v_add_f32_e32 v45, v45, v53
	v_cmp_gt_f32_e32 vcc, s82, v59
	v_exp_f32_e32 v45, v45
	v_sqrt_f32_e32 v61, v44
	v_mul_f32_e32 v57, v18, v22
	v_cndmask_b32_e32 v22, 0, v221, vcc
	v_add_f32_e32 v22, v59, v22
	v_exp_f32_e32 v22, v22
	v_ldexp_f32 v60, v45, v27
	v_mul_f32_e32 v18, v57, v61
	v_pk_fma_f32 v[44:45], v[56:57], v[60:61], v[18:19] op_sel_hi:[1,1,0]
	v_cndmask_b32_e32 v18, 0, v220, vcc
	v_ldexp_f32 v56, v22, v18
	v_and_b32_e32 v18, 0xffff0000, v17
	v_add_f32_e32 v18, v7, v18
	v_mul_f32_e32 v18, 0xbfb8aa3b, v18
	v_exp_f32_e32 v18, v18
	v_lshlrev_b32_e32 v17, 16, v17
	v_add_f32_e32 v17, v6, v17
	v_mul_f32_e32 v17, 0xbfb8aa3b, v17
	v_add_f32_e32 v18, 1.0, v18
	v_rcp_f32_e32 v18, v18
	v_exp_f32_e32 v17, v17
	v_and_b32_e32 v22, 0xffff0000, v21
	v_sqrt_f32_e32 v57, v51
	v_cmp_gt_f32_e32 vcc, s82, v49
	v_mul_f32_e32 v51, v18, v22
	v_add_f32_e32 v17, 1.0, v17
	v_cndmask_b32_e32 v22, 0, v221, vcc
	v_add_f32_e32 v22, v49, v22
	v_exp_f32_e32 v22, v22
	v_mul_f32_e32 v18, v51, v57
	v_rcp_f32_e32 v17, v17
	v_pk_fma_f32 v[60:61], v[50:51], v[56:57], v[18:19] op_sel_hi:[1,1,0]
	v_sqrt_f32_e32 v51, v58
	v_cndmask_b32_e32 v18, 0, v220, vcc
	v_ldexp_f32 v50, v22, v18
	v_lshlrev_b32_e32 v18, 16, v21
	v_mul_f32_e32 v49, v17, v18
	v_mul_f32_e32 v18, v49, v51
	v_cmp_gt_f32_e32 vcc, s82, v43
	v_pk_fma_f32 v[58:59], v[48:49], v[50:51], v[18:19] op_sel_hi:[1,1,0]
	v_sqrt_f32_e32 v49, v46
	v_cndmask_b32_e32 v18, 0, v221, vcc
	v_add_f32_e32 v18, v43, v18
	v_exp_f32_e32 v18, v18
	v_cndmask_b32_e32 v17, 0, v220, vcc
	v_mov_b32_e32 v50, v47
	v_cmp_gt_f32_e32 vcc, s82, v31
	v_ldexp_f32 v48, v18, v17
	v_and_b32_e32 v17, 0xffff0000, v16
	v_add_f32_e32 v17, v5, v17
	v_mul_f32_e32 v17, 0xbfb8aa3b, v17
	v_exp_f32_e32 v17, v17
	v_and_b32_e32 v18, 0xffff0000, v20
	v_add_f32_e32 v17, 1.0, v17
	v_rcp_f32_e32 v17, v17
	s_nop 0
	v_mul_f32_e32 v51, v17, v18
	v_lshlrev_b32_e32 v17, 16, v16
	v_mul_f32_e32 v18, v47, v48
	v_add_f32_e32 v17, v4, v17
	v_pk_fma_f32 v[62:63], v[50:51], v[48:49], v[18:19] op_sel_hi:[1,1,0]
	v_lshlrev_b32_e32 v18, 16, v20
	v_cndmask_b32_e32 v20, 0, v221, vcc
	v_mul_f32_e32 v17, 0xbfb8aa3b, v17
	v_add_f32_e32 v20, v31, v20
	v_exp_f32_e32 v17, v17
	v_exp_f32_e32 v20, v20
	v_cndmask_b32_e32 v16, 0, v220, vcc
	v_add_co_u32_e32 v48, vcc, s1, v38
	v_add_f32_e32 v17, 1.0, v17
	v_ldexp_f32 v16, v20, v16
	v_rcp_f32_e32 v20, v17
	v_sqrt_f32_e32 v17, v41
	v_addc_co_u32_e32 v49, vcc, 0, v39, vcc
	v_mul_f32_e32 v43, v20, v18
	v_mul_f32_e32 v18, v43, v17
	v_pk_fma_f32 v[56:57], v[42:43], v[16:17], v[18:19] op_sel_hi:[1,1,0]
	v_and_b32_e32 v16, 0xffff0000, v19
	v_add_f32_e32 v16, v15, v16
	v_mul_f32_e32 v16, 0xbfb8aa3b, v16
	v_exp_f32_e32 v16, v16
	v_and_b32_e32 v17, 0xffff0000, v23
	v_cvt_pk_bf16_f32 v18, v44, v52
	s_mov_b32 s1, 0x13e01000
	v_add_f32_e32 v16, 1.0, v16
	v_rcp_f32_e32 v16, v16
	s_nop 0
	v_mul_f32_e32 v41, v16, v17
	v_mul_f32_e32 v16, v41, v77
	v_pk_fma_f32 v[50:51], v[40:41], v[76:77], v[16:17] op_sel_hi:[1,1,0]
	v_cvt_pk_bf16_f32 v16, v56, v63
	v_cvt_pk_bf16_f32 v17, v58, v60
	v_cvt_pk_bf16_f32 v19, v54, v50
	global_store_dwordx4 v[24:25], v[16:19], off
	s_nop 1
	v_mov_b32_e32 v24, v162
	v_mov_b32_e32 v25, v163
	v_mov_b32_e32 v26, v164
	v_mov_b32_e32 v27, v165
	global_load_dwordx4 v[162:165], v[48:49], off offset:3584
	v_add_co_u32_e32 v40, vcc, s1, v38
	s_nop 0
	v_lshlrev_b32_e32 v31, 16, v24
	v_addc_co_u32_e32 v41, vcc, 0, v39, vcc
	v_add_co_u32_e32 v20, vcc, 0x8a01000, v38
	global_load_dwordx4 v[16:19], v[40:41], off offset:1024
	s_nop 0
	v_addc_co_u32_e32 v21, vcc, 0, v39, vcc
	global_load_dwordx4 v[20:23], v[20:21], off offset:1024
	v_add_f32_e32 v31, v0, v31
	v_mul_f32_e32 v31, 0xbfb8aa3b, v31
	v_exp_f32_e32 v31, v31
	s_nop 0
	v_add_f32_e32 v31, 1.0, v31
	v_rcp_f32_e32 v31, v31
	s_nop 0
	v_mul_f32_e32 v31, v74, v31
	v_mul_f32_e32 v42, 0x3fb17218, v31
	v_cmp_nlt_f32_e32 vcc, s5, v42
	s_and_saveexec_b64 s[2:3], vcc
	s_xor_b64 s[24:25], exec, s[2:3]
	v_mul_f32_e32 v42, 0x3fb8aa3b, v42
	v_exp_f32_e32 v42, v42
	s_nop 0
	v_sub_f32_e32 v51, 1.0, v42
	s_andn2_saveexec_b64 s[24:25], s[24:25]
	v_fmamk_f32 v43, v42, 0x3c088889, v202
	v_fmaak_f32 v43, v42, v43, 0x3e2aaaab
; __device__ __forceinline__ unsigned pk2(float lo, float hi) { f32x2_pk v = {lo, hi}; bf16x2_pk b = __builtin_convertvector(v, bf16x2_pk); return __builtin_bit_cast(unsigned, b); }
; __device__ __forceinline__ float sigmoidf_(float x) { return __builtin_amdgcn_rcpf(1.0f + __expf(-x)); }
; __device__ __forceinline__ void rg_unpack8(const u32x4 w, float* v) { v[0] = bflo(w.x); v[1] = bfhi(w.x); v[2] = bflo(w.y); v[3] = bfhi(w.y); v[4] = bflo(w.z); v[5] = bfhi(w.z); v[6] = bflo(w.w); v[7] = bfhi(w.w); }
; __device__ __forceinline__ void rg_ab(float ra, float ri, float x, float ba, float bx, float sp, float& a, float& b) {
;     const float r = sigmoidf_(ra + ba), ig = sigmoidf_(ri + bx); const float l2 = r * sp; a = exp2f(l2);
;     const float x2 = 1.3862943611198906f * l2;
;     const float om = x2 > -0.125f ? -x2 * (1.0f + x2 * (0.5f + x2 * (0.16666667f + x2 * (0.041666668f + x2 * 0.0083333338f)))) : 1.0f - __expf(x2);
;     b = __builtin_amdgcn_sqrtf(om) * (ig * x);
; }
; __device__ __forceinline__ void rg_scan2_phase(const bf16_t* RA0, bf16_t* RI0, const bf16_t* RA1, const bf16_t* RI1, const bf16_t* XCV, const float* bap, const float* bxp, const float* lamp, const float* CAR, bf16_t* Gb, int gtid, int ngt) {
;     ...
; #pragma unroll 4
;         for (int i = 0; i < 64; ++i) { const size_t off = (size_t)(row0 + i) * DRNN + 8 * cg;
;             float ra[8], ri[8], xv[8]; rg_unpack8(*(const u32x4*)(RA0 + off), ra); rg_unpack8(*(const u32x4*)(RI0 + off), ri); rg_unpack8(*(const u32x4*)(XCV + off), xv);
; #pragma unroll
;             for (int e = 0; e < 8; ++e) { float a, bb; rg_ab(ra[e], ri[e], xv[e], ba[e], bx[e], sp[e], a, bb); h[e] = a * h[e] + bb; }
;             u32x4 o; o.x = pk2(h[0], h[1]); o.y = pk2(h[2], h[3]); o.z = pk2(h[4], h[5]); o.w = pk2(h[6], h[7]); *(u32x4*)(RI0 + off) = o; }
	v_fma_f32 v43, v42, v43, 0.5
	v_fma_f32 v43, v42, v43, 1.0
	v_mul_f32_e64 v51, v43, -v42
	s_or_b64 exec, exec, s[24:25]
	v_and_b32_e32 v24, 0xffff0000, v24
	v_add_f32_e32 v24, v1, v24
	v_mul_f32_e32 v24, 0xbfb8aa3b, v24
	v_exp_f32_e32 v24, v24
	s_nop 0
	v_add_f32_e32 v24, 1.0, v24
	v_rcp_f32_e32 v24, v24
	s_nop 0
	v_mul_f32_e32 v57, v73, v24
	v_mul_f32_e32 v24, 0x3fb17218, v57
	v_cmp_nlt_f32_e32 vcc, s5, v24
	s_and_saveexec_b64 s[2:3], vcc
	s_xor_b64 s[24:25], exec, s[2:3]
	v_mul_f32_e32 v24, 0x3fb8aa3b, v24
	v_exp_f32_e32 v24, v24
	s_nop 0
	v_sub_f32_e32 v62, 1.0, v24
	s_andn2_saveexec_b64 s[24:25], s[24:25]
	v_fmamk_f32 v42, v24, 0x3c088889, v202
	v_fmaak_f32 v42, v24, v42, 0x3e2aaaab
	v_fma_f32 v42, v24, v42, 0.5
	v_fma_f32 v42, v24, v42, 1.0
	v_mul_f32_e64 v62, v42, -v24
	s_or_b64 exec, exec, s[24:25]
	v_lshlrev_b32_e32 v24, 16, v25
	v_add_f32_e32 v24, v2, v24
	v_mul_f32_e32 v24, 0xbfb8aa3b, v24
	v_exp_f32_e32 v24, v24
	s_nop 0
	v_add_f32_e32 v24, 1.0, v24
	v_rcp_f32_e32 v24, v24
	s_nop 0
	v_mul_f32_e32 v59, v71, v24
	v_mul_f32_e32 v24, 0x3fb17218, v59
	v_cmp_nlt_f32_e32 vcc, s5, v24
	s_and_saveexec_b64 s[2:3], vcc
	s_xor_b64 s[24:25], exec, s[2:3]
	v_mul_f32_e32 v24, 0x3fb8aa3b, v24
	v_exp_f32_e32 v24, v24
	s_nop 0
	v_sub_f32_e32 v76, 1.0, v24
	s_andn2_saveexec_b64 s[24:25], s[24:25]
	v_fmamk_f32 v42, v24, 0x3c088889, v202
	v_fmaak_f32 v42, v24, v42, 0x3e2aaaab
	v_fma_f32 v42, v24, v42, 0.5
	v_fma_f32 v42, v24, v42, 1.0
	v_mul_f32_e64 v76, v42, -v24
	s_or_b64 exec, exec, s[24:25]
	v_and_b32_e32 v24, 0xffff0000, v25
	v_add_f32_e32 v24, v3, v24
	v_mul_f32_e32 v24, 0xbfb8aa3b, v24
	v_exp_f32_e32 v24, v24
	s_nop 0
	v_add_f32_e32 v24, 1.0, v24
	v_rcp_f32_e32 v24, v24
	s_nop 0
	v_mul_f32_e32 v77, v70, v24
	v_mul_f32_e32 v24, 0x3fb17218, v77
	v_cmp_nlt_f32_e32 vcc, s5, v24
	s_and_saveexec_b64 s[2:3], vcc
	s_xor_b64 s[24:25], exec, s[2:3]
	v_mul_f32_e32 v24, 0x3fb8aa3b, v24
	v_exp_f32_e32 v24, v24
	s_nop 0
	v_sub_f32_e32 v61, 1.0, v24
	s_andn2_saveexec_b64 s[24:25], s[24:25]
	v_fmamk_f32 v25, v24, 0x3c088889, v202
	v_fmaak_f32 v25, v24, v25, 0x3e2aaaab
	v_fma_f32 v25, v24, v25, 0.5
	v_fma_f32 v25, v24, v25, 1.0
	v_mul_f32_e64 v61, v25, -v24
	s_or_b64 exec, exec, s[24:25]
	v_lshlrev_b32_e32 v24, 16, v26
	v_add_f32_e32 v24, v8, v24
	v_mul_f32_e32 v24, 0xbfb8aa3b, v24
	v_exp_f32_e32 v24, v24
	s_nop 0
	v_add_f32_e32 v24, 1.0, v24
	v_rcp_f32_e32 v24, v24
	s_nop 0
	v_mul_f32_e32 v78, v69, v24
	v_mul_f32_e32 v24, 0x3fb17218, v78
	v_cmp_nlt_f32_e32 vcc, s5, v24
	s_and_saveexec_b64 s[2:3], vcc
	s_xor_b64 s[24:25], exec, s[2:3]
	v_mul_f32_e32 v24, 0x3fb8aa3b, v24
	v_exp_f32_e32 v24, v24
	s_nop 0
	v_sub_f32_e32 v45, 1.0, v24
	s_andn2_saveexec_b64 s[24:25], s[24:25]
	v_fmamk_f32 v25, v24, 0x3c088889, v202
	v_fmaak_f32 v25, v24, v25, 0x3e2aaaab
	v_fma_f32 v25, v24, v25, 0.5
	v_fma_f32 v25, v24, v25, 1.0
	v_mul_f32_e64 v45, v25, -v24
	s_or_b64 exec, exec, s[24:25]
	v_and_b32_e32 v24, 0xffff0000, v26
	v_add_f32_e32 v24, v9, v24
	v_mul_f32_e32 v24, 0xbfb8aa3b, v24
	v_exp_f32_e32 v24, v24
	s_nop 0
	v_add_f32_e32 v24, 1.0, v24
	v_rcp_f32_e32 v24, v24
	s_nop 0
	v_mul_f32_e32 v47, v68, v24
	v_mul_f32_e32 v24, 0x3fb17218, v47
	v_cmp_nlt_f32_e32 vcc, s5, v24
	s_and_saveexec_b64 s[2:3], vcc
	s_xor_b64 s[24:25], exec, s[2:3]
	v_mul_f32_e32 v24, 0x3fb8aa3b, v24
	v_exp_f32_e32 v24, v24
	s_nop 0
	v_sub_f32_e32 v46, 1.0, v24
	s_andn2_saveexec_b64 s[24:25], s[24:25]
	v_fmamk_f32 v25, v24, 0x3c088889, v202
	v_fmaak_f32 v25, v24, v25, 0x3e2aaaab
	v_fma_f32 v25, v24, v25, 0.5
	v_fma_f32 v25, v24, v25, 1.0
	v_mul_f32_e64 v46, v25, -v24
	s_or_b64 exec, exec, s[24:25]
	v_lshlrev_b32_e32 v24, 16, v27
	v_add_f32_e32 v24, v10, v24
	v_mul_f32_e32 v24, 0xbfb8aa3b, v24
	v_exp_f32_e32 v24, v24
	s_nop 0
	v_add_f32_e32 v24, 1.0, v24
	v_rcp_f32_e32 v24, v24
	s_nop 0
	v_mul_f32_e32 v43, v67, v24
	v_mul_f32_e32 v24, 0x3fb17218, v43
	v_cmp_nlt_f32_e32 vcc, s5, v24
	s_and_saveexec_b64 s[2:3], vcc
	s_xor_b64 s[24:25], exec, s[2:3]
	v_mul_f32_e32 v24, 0x3fb8aa3b, v24
	v_exp_f32_e32 v24, v24
	s_nop 0
	v_sub_f32_e32 v42, 1.0, v24
	s_andn2_saveexec_b64 s[24:25], s[24:25]
	v_fmamk_f32 v25, v24, 0x3c088889, v202
	v_fmaak_f32 v25, v24, v25, 0x3e2aaaab
	v_fma_f32 v25, v24, v25, 0.5
	v_fma_f32 v25, v24, v25, 1.0
	v_mul_f32_e64 v42, v25, -v24
	s_or_b64 exec, exec, s[24:25]
	v_and_b32_e32 v24, 0xffff0000, v27
	v_add_f32_e32 v24, v11, v24
	v_mul_f32_e32 v24, 0xbfb8aa3b, v24
	v_exp_f32_e32 v24, v24
	s_nop 0
	v_add_f32_e32 v24, 1.0, v24
	v_rcp_f32_e32 v24, v24
	s_nop 0
	v_mul_f32_e32 v27, v75, v24
	v_mul_f32_e32 v24, 0x3fb17218, v27
	v_cmp_nlt_f32_e32 vcc, s5, v24
	s_and_saveexec_b64 s[2:3], vcc
	s_xor_b64 s[24:25], exec, s[2:3]
	v_mul_f32_e32 v24, 0x3fb8aa3b, v24
	v_exp_f32_e32 v24, v24
	s_nop 0
	v_sub_f32_e32 v26, 1.0, v24
	s_andn2_saveexec_b64 s[24:25], s[24:25]
	v_fmamk_f32 v25, v24, 0x3c088889, v202
	v_fmaak_f32 v25, v24, v25, 0x3e2aaaab
	v_fma_f32 v25, v24, v25, 0.5
	v_fma_f32 v25, v24, v25, 1.0
	v_mul_f32_e64 v26, v25, -v24
	s_or_b64 exec, exec, s[24:25]
	v_cmp_gt_f32_e32 vcc, s82, v43
	v_sqrt_f32_e32 v81, v42
	s_mov_b64 s[2:3], 0x13e01400
	v_cndmask_b32_e32 v55, 0, v221, vcc
	v_add_f32_e32 v43, v43, v55
	v_exp_f32_e32 v43, v43
	v_cndmask_b32_e32 v53, 0, v220, vcc
	v_cmp_gt_f32_e32 vcc, s82, v27
	v_lshl_add_u64 v[24:25], v[38:39], 0, s[2:3]
	v_ldexp_f32 v80, v43, v53
	s_waitcnt vmcnt(1)
	v_lshlrev_b32_e32 v43, 16, v19
	v_add_f32_e32 v43, v14, v43
	v_mul_f32_e32 v43, 0xbfb8aa3b, v43
	v_exp_f32_e32 v43, v43
	s_waitcnt vmcnt(0)
; __device__ __forceinline__ unsigned pk2(float lo, float hi) { f32x2_pk v = {lo, hi}; bf16x2_pk b = __builtin_convertvector(v, bf16x2_pk); return __builtin_bit_cast(unsigned, b); }
; __device__ __forceinline__ float sigmoidf_(float x) { return __builtin_amdgcn_rcpf(1.0f + __expf(-x)); }
; __device__ __forceinline__ void rg_unpack8(const u32x4 w, float* v) { v[0] = bflo(w.x); v[1] = bfhi(w.x); v[2] = bflo(w.y); v[3] = bfhi(w.y); v[4] = bflo(w.z); v[5] = bfhi(w.z); v[6] = bflo(w.w); v[7] = bfhi(w.w); }
; __device__ __forceinline__ void rg_ab(float ra, float ri, float x, float ba, float bx, float sp, float& a, float& b) {
;     const float r = sigmoidf_(ra + ba), ig = sigmoidf_(ri + bx); const float l2 = r * sp; a = exp2f(l2);
;     const float x2 = 1.3862943611198906f * l2;
;     const float om = x2 > -0.125f ? -x2 * (1.0f + x2 * (0.5f + x2 * (0.16666667f + x2 * (0.041666668f + x2 * 0.0083333338f)))) : 1.0f - __expf(x2);
;     b = __builtin_amdgcn_sqrtf(om) * (ig * x);
; }
; __device__ __forceinline__ void rg_scan2_phase(const bf16_t* RA0, bf16_t* RI0, const bf16_t* RA1, const bf16_t* RI1, const bf16_t* XCV, const float* bap, const float* bxp, const float* lamp, const float* CAR, bf16_t* Gb, int gtid, int ngt) {
;     ...
; #pragma unroll 4
;         for (int i = 0; i < 64; ++i) { const size_t off = (size_t)(row0 + i) * DRNN + 8 * cg;
;             float ra[8], ri[8], xv[8]; rg_unpack8(*(const u32x4*)(RA0 + off), ra); rg_unpack8(*(const u32x4*)(RI0 + off), ri); rg_unpack8(*(const u32x4*)(XCV + off), xv);
; #pragma unroll
;             for (int e = 0; e < 8; ++e) { float a, bb; rg_ab(ra[e], ri[e], xv[e], ba[e], bx[e], sp[e], a, bb); h[e] = a * h[e] + bb; }
;             u32x4 o; o.x = pk2(h[0], h[1]); o.y = pk2(h[2], h[3]); o.z = pk2(h[4], h[5]); o.w = pk2(h[6], h[7]); *(u32x4*)(RI0 + off) = o; }
	v_lshlrev_b32_e32 v53, 16, v23
	v_add_f32_e32 v43, 1.0, v43
	v_rcp_f32_e32 v43, v43
	s_nop 0
	v_mul_f32_e32 v55, v43, v53
	v_cndmask_b32_e32 v53, 0, v221, vcc
	v_add_f32_e32 v27, v27, v53
	v_exp_f32_e32 v27, v27
	v_mul_f32_e32 v42, v55, v81
	v_pk_fma_f32 v[42:43], v[54:55], v[80:81], v[42:43] op_sel_hi:[1,1,0]
	v_sqrt_f32_e32 v81, v46
	v_cndmask_b32_e32 v43, 0, v220, vcc
	v_cmp_gt_f32_e32 vcc, s82, v47
	v_ldexp_f32 v54, v27, v43
	v_sqrt_f32_e32 v55, v26
	v_cndmask_b32_e32 v43, 0, v221, vcc
	v_add_f32_e32 v43, v47, v43
	v_exp_f32_e32 v43, v43
	v_cndmask_b32_e32 v27, 0, v220, vcc
	v_cmp_gt_f32_e32 vcc, s82, v78
	v_ldexp_f32 v80, v43, v27
	v_and_b32_e32 v27, 0xffff0000, v18
	v_add_f32_e32 v27, v13, v27
	v_mul_f32_e32 v27, 0xbfb8aa3b, v27
	v_lshlrev_b32_e32 v18, 16, v18
	v_exp_f32_e32 v27, v27
	v_add_f32_e32 v18, v12, v18
	v_mul_f32_e32 v18, 0xbfb8aa3b, v18
	v_exp_f32_e32 v18, v18
	v_add_f32_e32 v27, 1.0, v27
	v_rcp_f32_e32 v27, v27
	v_and_b32_e32 v43, 0xffff0000, v22
	v_add_f32_e32 v18, 1.0, v18
	v_rcp_f32_e32 v18, v18
	v_mul_f32_e32 v53, v27, v43
	v_cndmask_b32_e32 v43, 0, v221, vcc
	v_mul_f32_e32 v46, v53, v81
	v_cndmask_b32_e32 v27, 0, v220, vcc
	v_add_f32_e32 v43, v78, v43
	v_lshlrev_b32_e32 v22, 16, v22
	v_cmp_gt_f32_e32 vcc, s82, v77
	v_pk_fma_f32 v[46:47], v[52:53], v[80:81], v[46:47] op_sel_hi:[1,1,0]
	v_exp_f32_e32 v43, v43
	v_sqrt_f32_e32 v53, v45
	v_mul_f32_e32 v45, v18, v22
	v_cndmask_b32_e32 v22, 0, v221, vcc
	v_add_f32_e32 v22, v77, v22
	v_exp_f32_e32 v22, v22
	v_ldexp_f32 v52, v43, v27
	v_mul_f32_e32 v18, v45, v53
	v_pk_fma_f32 v[52:53], v[44:45], v[52:53], v[18:19] op_sel_hi:[1,1,0]
	v_cndmask_b32_e32 v18, 0, v220, vcc
	v_ldexp_f32 v44, v22, v18
	v_and_b32_e32 v18, 0xffff0000, v17
	v_add_f32_e32 v18, v7, v18
	v_mul_f32_e32 v18, 0xbfb8aa3b, v18
	v_exp_f32_e32 v18, v18
	v_lshlrev_b32_e32 v17, 16, v17
	v_add_f32_e32 v17, v6, v17
	v_mul_f32_e32 v17, 0xbfb8aa3b, v17
	v_add_f32_e32 v18, 1.0, v18
	v_rcp_f32_e32 v18, v18
	v_exp_f32_e32 v17, v17
	v_and_b32_e32 v22, 0xffff0000, v21
	v_sqrt_f32_e32 v45, v61
	v_cmp_gt_f32_e32 vcc, s82, v59
	v_mul_f32_e32 v61, v18, v22
	v_add_f32_e32 v17, 1.0, v17
	v_cndmask_b32_e32 v22, 0, v221, vcc
	v_add_f32_e32 v22, v59, v22
	v_exp_f32_e32 v22, v22
	v_mul_f32_e32 v18, v61, v45
	v_rcp_f32_e32 v17, v17
	v_pk_fma_f32 v[60:61], v[60:61], v[44:45], v[18:19] op_sel_hi:[1,1,0]
	v_sqrt_f32_e32 v45, v76
	v_cndmask_b32_e32 v18, 0, v220, vcc
	v_ldexp_f32 v44, v22, v18
	v_lshlrev_b32_e32 v18, 16, v21
	v_mul_f32_e32 v59, v17, v18
	v_mul_f32_e32 v18, v59, v45
	v_cmp_gt_f32_e32 vcc, s82, v57
	v_pk_fma_f32 v[44:45], v[58:59], v[44:45], v[18:19] op_sel_hi:[1,1,0]
	v_sqrt_f32_e32 v59, v62
	v_cndmask_b32_e32 v18, 0, v221, vcc
	v_add_f32_e32 v18, v57, v18
	v_exp_f32_e32 v18, v18
	v_cndmask_b32_e32 v17, 0, v220, vcc
	v_mov_b32_e32 v76, v63
	v_cmp_gt_f32_e32 vcc, s82, v31
	v_ldexp_f32 v58, v18, v17
	v_and_b32_e32 v17, 0xffff0000, v16
	v_add_f32_e32 v17, v5, v17
	v_mul_f32_e32 v17, 0xbfb8aa3b, v17
	v_exp_f32_e32 v17, v17
	v_and_b32_e32 v18, 0xffff0000, v20
	v_add_f32_e32 v17, 1.0, v17
	v_rcp_f32_e32 v17, v17
	s_nop 0
	v_mul_f32_e32 v77, v17, v18
	v_lshlrev_b32_e32 v17, 16, v16
	v_mul_f32_e32 v18, v63, v58
	v_add_f32_e32 v17, v4, v17
	v_pk_fma_f32 v[58:59], v[76:77], v[58:59], v[18:19] op_sel_hi:[1,1,0]
	v_lshlrev_b32_e32 v18, 16, v20
	v_cndmask_b32_e32 v20, 0, v221, vcc
	v_mul_f32_e32 v17, 0xbfb8aa3b, v17
	v_add_f32_e32 v20, v31, v20
	v_exp_f32_e32 v17, v17
	v_exp_f32_e32 v20, v20
	v_cndmask_b32_e32 v16, 0, v220, vcc
	v_add_f32_e32 v17, 1.0, v17
	v_ldexp_f32 v16, v20, v16
	v_rcp_f32_e32 v20, v17
	v_sqrt_f32_e32 v17, v51
	v_mul_f32_e32 v57, v20, v18
	v_mul_f32_e32 v18, v57, v17
	v_pk_fma_f32 v[56:57], v[56:57], v[16:17], v[18:19] op_sel_hi:[1,1,0]
	v_and_b32_e32 v16, 0xffff0000, v19
	v_add_f32_e32 v16, v15, v16
	v_mul_f32_e32 v16, 0xbfb8aa3b, v16
	v_exp_f32_e32 v16, v16
	v_and_b32_e32 v17, 0xffff0000, v23
	v_cvt_pk_bf16_f32 v18, v52, v46
	global_load_dwordx4 v[20:23], v[40:41], off offset:3584
	v_add_f32_e32 v16, 1.0, v16
	v_rcp_f32_e32 v16, v16
	s_nop 0
	v_mul_f32_e32 v51, v16, v17
	v_mul_f32_e32 v16, v51, v55
	v_pk_fma_f32 v[54:55], v[50:51], v[54:55], v[16:17] op_sel_hi:[1,1,0]
	v_cvt_pk_bf16_f32 v16, v56, v59
	v_cvt_pk_bf16_f32 v17, v44, v60
	v_cvt_pk_bf16_f32 v19, v42, v54
	global_store_dwordx4 v[24:25], v[16:19], off
	s_nop 1
	v_mov_b32_e32 v24, v162
	v_mov_b32_e32 v25, v163
	v_mov_b32_e32 v26, v164
	v_mov_b32_e32 v27, v165
	v_lshl_add_u64 v[166:167], v[48:49], 0, s[100:101]
	global_load_dwordx4 v[162:165], v[166:167], off offset:2048
	s_waitcnt vmcnt(1)
; __device__ __forceinline__ unsigned pk2(float lo, float hi) { f32x2_pk v = {lo, hi}; bf16x2_pk b = __builtin_convertvector(v, bf16x2_pk); return __builtin_bit_cast(unsigned, b); }
; __device__ __forceinline__ float sigmoidf_(float x) { return __builtin_amdgcn_rcpf(1.0f + __expf(-x)); }
; __device__ __forceinline__ void rg_unpack8(const u32x4 w, float* v) { v[0] = bflo(w.x); v[1] = bfhi(w.x); v[2] = bflo(w.y); v[3] = bfhi(w.y); v[4] = bflo(w.z); v[5] = bfhi(w.z); v[6] = bflo(w.w); v[7] = bfhi(w.w); }
; __device__ __forceinline__ void rg_ab(float ra, float ri, float x, float ba, float bx, float sp, float& a, float& b) {
;     const float r = sigmoidf_(ra + ba), ig = sigmoidf_(ri + bx); const float l2 = r * sp; a = exp2f(l2);
;     const float x2 = 1.3862943611198906f * l2;
;     const float om = x2 > -0.125f ? -x2 * (1.0f + x2 * (0.5f + x2 * (0.16666667f + x2 * (0.041666668f + x2 * 0.0083333338f)))) : 1.0f - __expf(x2);
;     b = __builtin_amdgcn_sqrtf(om) * (ig * x);
; }
; __device__ __forceinline__ void rg_scan2_phase(const bf16_t* RA0, bf16_t* RI0, const bf16_t* RA1, const bf16_t* RI1, const bf16_t* XCV, const float* bap, const float* bxp, const float* lamp, const float* CAR, bf16_t* Gb, int gtid, int ngt) {
;     ...
; #pragma unroll 4
;         for (int i = 0; i < 64; ++i) { const size_t off = (size_t)(row0 + i) * DRNN + 8 * cg;
;             float ra[8], ri[8], xv[8]; rg_unpack8(*(const u32x4*)(RA0 + off), ra); rg_unpack8(*(const u32x4*)(RI0 + off), ri); rg_unpack8(*(const u32x4*)(XCV + off), xv);
; #pragma unroll
;             for (int e = 0; e < 8; ++e) { float a, bb; rg_ab(ra[e], ri[e], xv[e], ba[e], bx[e], sp[e], a, bb); h[e] = a * h[e] + bb; }
;             u32x4 o; o.x = pk2(h[0], h[1]); o.y = pk2(h[2], h[3]); o.z = pk2(h[4], h[5]); o.w = pk2(h[6], h[7]); *(u32x4*)(RI0 + off) = o; }
	v_lshlrev_b32_e32 v31, 16, v24
	v_add_co_u32_e32 v16, vcc, 0x8a01000, v38
	v_add_f32_e32 v31, v0, v31
	s_nop 0
	v_addc_co_u32_e32 v17, vcc, 0, v39, vcc
	global_load_dwordx4 v[16:19], v[16:17], off offset:3584
	v_mul_f32_e32 v31, 0xbfb8aa3b, v31
	v_exp_f32_e32 v31, v31
	s_nop 0
	v_add_f32_e32 v31, 1.0, v31
	v_rcp_f32_e32 v31, v31
	s_nop 0
	v_mul_f32_e32 v31, v74, v31
	v_mul_f32_e32 v41, 0x3fb17218, v31
	v_cmp_nlt_f32_e32 vcc, s5, v41
	s_and_saveexec_b64 s[2:3], vcc
	s_xor_b64 s[24:25], exec, s[2:3]
	v_mul_f32_e32 v40, 0x3fb8aa3b, v41
	v_exp_f32_e32 v40, v40
	s_nop 0
	v_sub_f32_e32 v40, 1.0, v40
	s_andn2_saveexec_b64 s[24:25], s[24:25]
	v_fmamk_f32 v40, v41, 0x3c088889, v202
	v_fmaak_f32 v40, v41, v40, 0x3e2aaaab
	v_fma_f32 v40, v41, v40, 0.5
	v_fma_f32 v40, v41, v40, 1.0
	v_mul_f32_e64 v40, v40, -v41
	s_or_b64 exec, exec, s[24:25]
	v_and_b32_e32 v24, 0xffff0000, v24
	v_add_f32_e32 v24, v1, v24
	v_mul_f32_e32 v24, 0xbfb8aa3b, v24
	v_exp_f32_e32 v24, v24
	s_nop 0
	v_add_f32_e32 v24, 1.0, v24
	v_rcp_f32_e32 v24, v24
	s_nop 0
	v_mul_f32_e32 v24, v73, v24
	v_mul_f32_e32 v41, 0x3fb17218, v24
	v_cmp_nlt_f32_e32 vcc, s5, v41
	s_and_saveexec_b64 s[2:3], vcc
	s_xor_b64 s[24:25], exec, s[2:3]
	v_mul_f32_e32 v41, 0x3fb8aa3b, v41
	v_exp_f32_e32 v41, v41
	s_nop 0
	v_sub_f32_e32 v43, 1.0, v41
	s_andn2_saveexec_b64 s[24:25], s[24:25]
	v_fmamk_f32 v43, v41, 0x3c088889, v202
	v_fmaak_f32 v43, v41, v43, 0x3e2aaaab
	v_fma_f32 v43, v41, v43, 0.5
	v_fma_f32 v43, v41, v43, 1.0
	v_mul_f32_e64 v43, v43, -v41
	s_or_b64 exec, exec, s[24:25]
	v_lshlrev_b32_e32 v41, 16, v25
	v_add_f32_e32 v41, v2, v41
	v_mul_f32_e32 v41, 0xbfb8aa3b, v41
	v_exp_f32_e32 v41, v41
	s_nop 0
	v_add_f32_e32 v41, 1.0, v41
	v_rcp_f32_e32 v41, v41
	s_nop 0
	v_mul_f32_e32 v45, v71, v41
	v_mul_f32_e32 v41, 0x3fb17218, v45
	v_cmp_nlt_f32_e32 vcc, s5, v41
	s_and_saveexec_b64 s[2:3], vcc
	s_xor_b64 s[24:25], exec, s[2:3]
	v_mul_f32_e32 v41, 0x3fb8aa3b, v41
	v_exp_f32_e32 v41, v41
	s_nop 0
	v_sub_f32_e32 v47, 1.0, v41
	s_andn2_saveexec_b64 s[24:25], s[24:25]
	v_fmamk_f32 v47, v41, 0x3c088889, v202
	v_fmaak_f32 v47, v41, v47, 0x3e2aaaab
	v_fma_f32 v47, v41, v47, 0.5
	v_fma_f32 v47, v41, v47, 1.0
	v_mul_f32_e64 v47, v47, -v41
	s_or_b64 exec, exec, s[24:25]
	v_and_b32_e32 v25, 0xffff0000, v25
	v_add_f32_e32 v25, v3, v25
	v_mul_f32_e32 v25, 0xbfb8aa3b, v25
	v_exp_f32_e32 v25, v25
	s_nop 0
	v_add_f32_e32 v25, 1.0, v25
	v_rcp_f32_e32 v25, v25
	s_nop 0
	v_mul_f32_e32 v25, v70, v25
	v_mul_f32_e32 v41, 0x3fb17218, v25
	v_cmp_nlt_f32_e32 vcc, s5, v41
	s_and_saveexec_b64 s[2:3], vcc
	s_xor_b64 s[24:25], exec, s[2:3]
	v_mul_f32_e32 v41, 0x3fb8aa3b, v41
	v_exp_f32_e32 v41, v41
	s_nop 0
	v_sub_f32_e32 v48, 1.0, v41
	s_andn2_saveexec_b64 s[24:25], s[24:25]
	v_fmamk_f32 v48, v41, 0x3c088889, v202
	v_fmaak_f32 v48, v41, v48, 0x3e2aaaab
	v_fma_f32 v48, v41, v48, 0.5
	v_fma_f32 v48, v41, v48, 1.0
	v_mul_f32_e64 v48, v48, -v41
	s_or_b64 exec, exec, s[24:25]
	v_lshlrev_b32_e32 v41, 16, v26
	v_add_f32_e32 v41, v8, v41
	v_mul_f32_e32 v41, 0xbfb8aa3b, v41
	v_exp_f32_e32 v41, v41
	s_nop 0
	v_add_f32_e32 v41, 1.0, v41
	v_rcp_f32_e32 v41, v41
	s_nop 0
	v_mul_f32_e32 v49, v69, v41
	v_mul_f32_e32 v41, 0x3fb17218, v49
	v_cmp_nlt_f32_e32 vcc, s5, v41
	s_and_saveexec_b64 s[2:3], vcc
	s_xor_b64 s[24:25], exec, s[2:3]
	v_mul_f32_e32 v41, 0x3fb8aa3b, v41
	v_exp_f32_e32 v41, v41
	s_nop 0
	v_sub_f32_e32 v53, 1.0, v41
	s_andn2_saveexec_b64 s[24:25], s[24:25]
	v_fmamk_f32 v50, v41, 0x3c088889, v202
	v_fmaak_f32 v50, v41, v50, 0x3e2aaaab
	v_fma_f32 v50, v41, v50, 0.5
	v_fma_f32 v50, v41, v50, 1.0
	v_mul_f32_e64 v53, v50, -v41
	s_or_b64 exec, exec, s[24:25]
	v_and_b32_e32 v26, 0xffff0000, v26
	v_add_f32_e32 v26, v9, v26
	v_mul_f32_e32 v26, 0xbfb8aa3b, v26
	v_exp_f32_e32 v26, v26
	s_nop 0
	v_add_f32_e32 v26, 1.0, v26
	v_rcp_f32_e32 v26, v26
	s_nop 0
	v_mul_f32_e32 v26, v68, v26
	v_mul_f32_e32 v41, 0x3fb17218, v26
	v_cmp_nlt_f32_e32 vcc, s5, v41
	s_and_saveexec_b64 s[2:3], vcc
	s_xor_b64 s[24:25], exec, s[2:3]
	v_mul_f32_e32 v41, 0x3fb8aa3b, v41
	v_exp_f32_e32 v41, v41
	s_nop 0
	v_sub_f32_e32 v55, 1.0, v41
	s_andn2_saveexec_b64 s[24:25], s[24:25]
	v_fmamk_f32 v50, v41, 0x3c088889, v202
	v_fmaak_f32 v50, v41, v50, 0x3e2aaaab
	v_fma_f32 v50, v41, v50, 0.5
	v_fma_f32 v50, v41, v50, 1.0
	v_mul_f32_e64 v55, v50, -v41
	s_or_b64 exec, exec, s[24:25]
	v_lshlrev_b32_e32 v41, 16, v27
	v_add_f32_e32 v41, v10, v41
	v_mul_f32_e32 v41, 0xbfb8aa3b, v41
	v_exp_f32_e32 v41, v41
	s_nop 0
	v_add_f32_e32 v41, 1.0, v41
	v_rcp_f32_e32 v41, v41
	s_nop 0
	v_mul_f32_e32 v58, v67, v41
	v_mul_f32_e32 v41, 0x3fb17218, v58
	v_cmp_nlt_f32_e32 vcc, s5, v41
	s_and_saveexec_b64 s[2:3], vcc
	s_xor_b64 s[24:25], exec, s[2:3]
	v_mul_f32_e32 v41, 0x3fb8aa3b, v41
	v_exp_f32_e32 v41, v41
	s_nop 0
	v_sub_f32_e32 v62, 1.0, v41
	s_andn2_saveexec_b64 s[24:25], s[24:25]
	v_fmamk_f32 v50, v41, 0x3c088889, v202
	v_fmaak_f32 v50, v41, v50, 0x3e2aaaab
	v_fma_f32 v50, v41, v50, 0.5
	v_fma_f32 v50, v41, v50, 1.0
	v_mul_f32_e64 v62, v50, -v41
	s_or_b64 exec, exec, s[24:25]
	v_and_b32_e32 v27, 0xffff0000, v27
	v_add_f32_e32 v27, v11, v27
	v_mul_f32_e32 v27, 0xbfb8aa3b, v27
	v_exp_f32_e32 v27, v27
	s_nop 0
	v_add_f32_e32 v27, 1.0, v27
	v_rcp_f32_e32 v27, v27
	s_nop 0
	v_mul_f32_e32 v27, v75, v27
	v_mul_f32_e32 v41, 0x3fb17218, v27
	v_cmp_nlt_f32_e32 vcc, s5, v41
	s_and_saveexec_b64 s[2:3], vcc
	s_xor_b64 s[24:25], exec, s[2:3]
	v_mul_f32_e32 v41, 0x3fb8aa3b, v41
	v_exp_f32_e32 v41, v41
	s_nop 0
	v_sub_f32_e32 v63, 1.0, v41
	s_andn2_saveexec_b64 s[24:25], s[24:25]
	s_cbranch_execz .LBB0_1250
	v_fmamk_f32 v50, v41, 0x3c088889, v202
	v_fmaak_f32 v50, v41, v50, 0x3e2aaaab
	v_fma_f32 v50, v41, v50, 0.5
	v_fma_f32 v50, v41, v50, 1.0
	v_mul_f32_e64 v63, v50, -v41
	s_branch .LBB0_1250
